# attention items: first K/V tile's 8 loads issued right after the prologue barrier together with the q/lambda batch (one exposed round trip fewer per item)
# baseline (speedup 1.0000x reference)
.LBB0_696:
	s_andn2_b64 vcc, exec, s[36:37]
	s_cbranch_vccnz .LBB0_703
	v_mov_b32_e32 v50, v189
	s_lshl_b32 s20, s19, 4
	v_readlane_b32 s38, v251, 47
	v_and_b32_e32 v0, 63, v50
	s_and_b32 s23, s20, 0x7f00
	s_lshl_b32 s36, s19, 6
	v_lshlrev_b32_e32 v0, 2, v0
	v_readlane_b32 s39, v251, 48
	s_add_i32 s37, s23, 0xffffc000
	s_and_b32 s20, s36, 0xc0
	s_nop 2
	global_load_dword v18, v0, s[38:39]
	global_load_dword v19, v0, s[38:39] offset:256
	global_load_dword v20, v0, s[38:39] offset:512
	global_load_dword v21, v0, s[38:39] offset:768
	v_ashrrev_i32_e32 v0, 2, v50
	s_or_b32 s20, s37, s20
	v_and_b32_e32 v184, -16, v0
	s_lshl_b32 s21, s19, 5
	v_and_b32_e32 v183, 15, v50
	v_add_u32_e32 v0, s20, v184
	s_and_b32 s21, s21, 0x180
	v_or_b32_e32 v0, v0, v183
	v_mov_b64_e32 v[16:17], s[6:7]
	v_mad_i64_i32 v[0:1], s[38:39], v0, s0, v[16:17]
	s_lshl_b32 s70, s21, 1
	v_lshl_add_u64 v[0:1], v[0:1], 0, s[70:71]
	v_and_b32_e32 v160, 48, v50
	v_lshl_add_u64 v[4:5], v[0:1], 0, v[160:161]
	s_movk_i32 s42, 0x1000
	v_add_co_u32_e32 v0, vcc, s42, v4
	v_mbcnt_hi_u32_b32 v151, -1, v194
	s_nop 0
	v_addc_co_u32_e32 v1, vcc, 0, v5, vcc
	global_load_dwordx4 v[0:3], v[0:1], off offset:1024
	v_and_b32_e32 v8, 64, v151
	s_mov_b64 s[38:39], 0x1400
	v_xor_b32_e32 v9, 32, v151
	v_add_u32_e32 v187, 64, v8
	v_lshl_add_u64 v[12:13], v[4:5], 0, s[38:39]
	v_xor_b32_e32 v10, 16, v151
	v_cmp_lt_i32_e32 vcc, v9, v187
	global_load_dwordx4 v[4:7], v[12:13], off offset:64
	v_xor_b32_e32 v11, 8, v151
	v_cndmask_b32_e32 v8, v151, v9, vcc
	v_cmp_lt_i32_e32 vcc, v10, v187
	v_lshlrev_b32_e32 v181, 2, v8
	s_mov_b32 s44, 0x3e000000
	v_cndmask_b32_e32 v9, v151, v10, vcc
	v_cmp_lt_i32_e32 vcc, v11, v187
	v_lshlrev_b32_e32 v182, 2, v9
	v_xor_b32_e32 v14, 4, v151
	v_cndmask_b32_e32 v10, v151, v11, vcc
	v_lshlrev_b32_e32 v24, 2, v10
	global_load_dwordx4 v[8:11], v[12:13], off offset:128
	v_cmp_lt_i32_e32 vcc, v14, v187
	v_xor_b32_e32 v15, 2, v151
	v_ashrrev_i32_e32 v185, 4, v50
	v_cndmask_b32_e32 v14, v151, v14, vcc
	v_lshlrev_b32_e32 v27, 2, v14
	v_cmp_lt_i32_e32 vcc, v15, v187
	v_lshlrev_b32_e32 v48, 4, v183
	v_mov_b32_e32 v49, v161
	v_cndmask_b32_e32 v15, v151, v15, vcc
	v_lshlrev_b32_e32 v28, 2, v15
	global_load_dwordx4 v[12:15], v[12:13], off offset:192
	s_barrier
	s_movk_i32 s39, 0x120
	v_mul_lo_u32 v211, v185, s39
	s_add_i32 s38, s23, 0xffffc040
	v_lshlrev_b32_e32 v186, 3, v50
	v_and_b32_e32 v84, 24, v186
	s_mov_b32 s22, 0
	v_mov_b32_e32 v142, 0xf149f2ca
	v_mov_b32_e32 v112, 0xf149f2ca
	s_waitcnt vmcnt(8)
	v_add_u32_e32 v86, s37, v185
	v_mad_i64_i32 v[90:91], s[40:41], v86, s0, v[16:17]
	v_lshl_add_u64 v[92:93], v[90:91], 0, s[70:71]
	v_lshl_add_u64 v[94:95], v[92:93], 0, v[48:49]
	v_add_co_u32_e32 v88, vcc, s42, v94
	s_nop 1
	v_addc_co_u32_e32 v89, vcc, 0, v95, vcc
	global_load_dwordx4 v[96:99], v[88:89], off offset:2048
	global_load_dwordx4 v[100:103], v[88:89], off offset:3072
	v_add_u32_e32 v104, 0x100, v50
	v_ashrrev_i32_e32 v180, 4, v104
	v_add_u32_e32 v104, s37, v180
	v_mad_i64_i32 v[108:109], s[40:41], v104, s0, v[16:17]
	v_lshl_add_u64 v[110:111], v[108:109], 0, s[70:71]
	v_lshl_add_u64 v[114:115], v[110:111], 0, v[48:49]
	v_add_co_u32_e32 v106, vcc, s42, v114
	s_nop 1
	v_addc_co_u32_e32 v107, vcc, 0, v115, vcc
	global_load_dwordx4 v[116:119], v[106:107], off offset:2048
	global_load_dwordx4 v[120:123], v[106:107], off offset:3072
	v_add_u32_e32 v124, 0x200, v50
	v_ashrrev_i32_e32 v179, 4, v124
	v_add_u32_e32 v124, s37, v179
	v_mad_i64_i32 v[128:129], s[40:41], v124, s0, v[16:17]
	v_lshl_add_u64 v[130:131], v[128:129], 0, s[70:71]
	v_lshl_add_u64 v[132:133], v[130:131], 0, v[48:49]
	v_add_co_u32_e32 v126, vcc, s42, v132
	s_nop 1
	v_addc_co_u32_e32 v127, vcc, 0, v133, vcc
	global_load_dwordx4 v[134:137], v[126:127], off offset:2048
	global_load_dwordx4 v[138:141], v[126:127], off offset:3072
	v_add_u32_e32 v216, 0x300, v50
	v_ashrrev_i32_e32 v178, 4, v216
	v_add_u32_e32 v216, s37, v178
	v_mad_i64_i32 v[220:221], s[40:41], v216, s0, v[16:17]
	v_lshl_add_u64 v[222:223], v[220:221], 0, s[70:71]
	v_lshl_add_u64 v[224:225], v[222:223], 0, v[48:49]
	v_add_co_u32_e32 v218, vcc, s42, v224
	s_nop 1
	v_addc_co_u32_e32 v219, vcc, 0, v225, vcc
	global_load_dwordx4 v[226:229], v[218:219], off offset:2048
	global_load_dwordx4 v[230:233], v[218:219], off offset:3072
	s_waitcnt vmcnt(14)
	v_mul_f32_e32 v22, v18, v19
	ds_bpermute_b32 v25, v181, v22
	s_waitcnt vmcnt(12)
	v_mul_f32_e32 v23, v20, v21
	ds_bpermute_b32 v26, v181, v23
	s_waitcnt lgkmcnt(1)
	v_fmac_f32_e32 v25, v18, v19
	ds_bpermute_b32 v29, v182, v25
	s_waitcnt lgkmcnt(1)
	v_fmac_f32_e32 v26, v20, v21
	ds_bpermute_b32 v30, v182, v26
	s_waitcnt vmcnt(11)
	v_and_b32_e32 v19, 0xffff0000, v0
	v_lshlrev_b32_e32 v18, 16, v0
	v_and_b32_e32 v21, 0xffff0000, v1
	v_lshlrev_b32_e32 v20, 16, v1
	v_and_b32_e32 v1, 0xffff0000, v2
	v_lshlrev_b32_e32 v0, 16, v2
	v_and_b32_e32 v23, 0xffff0000, v3
	v_lshlrev_b32_e32 v22, 16, v3
	v_pk_mul_f32 v[2:3], v[18:19], s[44:45] op_sel_hi:[1,0]
	v_pk_mul_f32 v[0:1], v[0:1], s[44:45] op_sel_hi:[1,0]
	v_cvt_pk_bf16_f32 v51, v2, v3
	s_waitcnt lgkmcnt(1)
	v_add_f32_e32 v2, v25, v29
	s_waitcnt lgkmcnt(0)
	v_add_f32_e32 v3, v26, v30
	ds_bpermute_b32 v25, v24, v2
	ds_bpermute_b32 v24, v24, v3
	v_bfe_u32 v32, v0, 16, 1
	v_add3_u32 v55, v0, v32, s94
	v_pk_mul_f32 v[18:19], v[20:21], s[44:45] op_sel_hi:[1,0]
	s_waitcnt lgkmcnt(1)
	v_add_f32_e32 v0, v2, v25
	s_waitcnt lgkmcnt(0)
	v_add_f32_e32 v2, v3, v24
	ds_bpermute_b32 v3, v27, v0
	v_bfe_u32 v34, v18, 16, 1
	v_add3_u32 v53, v18, v34, s94
	ds_bpermute_b32 v18, v27, v2
	v_bfe_u32 v31, v1, 16, 1
	v_add3_u32 v56, v1, v31, s94
	s_waitcnt lgkmcnt(1)
	v_add_f32_e32 v205, v0, v3
	s_waitcnt vmcnt(10)
	v_and_b32_e32 v1, 0xffff0000, v4
	v_lshlrev_b32_e32 v0, 16, v4
	v_bfe_u32 v33, v19, 16, 1
	v_pk_mul_f32 v[0:1], v[0:1], s[44:45] op_sel_hi:[1,0]
	v_add3_u32 v54, v19, v33, s94
	s_waitcnt lgkmcnt(0)
	v_add_f32_e32 v207, v2, v18
	v_and_b32_e32 v19, 0xffff0000, v7
	v_lshlrev_b32_e32 v18, 16, v7
	v_and_b32_e32 v3, 0xffff0000, v5
	v_lshlrev_b32_e32 v2, 16, v5
	v_and_b32_e32 v5, 0xffff0000, v6
	v_lshlrev_b32_e32 v4, 16, v6
	v_pk_mul_f32 v[6:7], v[18:19], s[44:45] op_sel_hi:[1,0]
	v_cvt_pk_bf16_f32 v60, v0, v1
	s_waitcnt vmcnt(9)
	v_and_b32_e32 v1, 0xffff0000, v8
	v_lshlrev_b32_e32 v0, 16, v8
	v_pk_mul_f32 v[42:43], v[0:1], s[44:45] op_sel_hi:[1,0]
	v_and_b32_e32 v1, 0xffff0000, v9
	v_lshlrev_b32_e32 v0, 16, v9
	v_pk_mul_f32 v[8:9], v[0:1], s[44:45] op_sel_hi:[1,0]
	s_nop 0
	v_add_u32_e32 v18, 0x100, v50
	v_pk_mul_f32 v[20:21], v[22:23], s[44:45] op_sel_hi:[1,0]
	s_nop 0
	v_ashrrev_i32_e32 v180, 4, v18
	v_pk_mul_f32 v[4:5], v[4:5], s[44:45] op_sel_hi:[1,0]
	s_nop 0
	s_nop 0
	v_add_u32_e32 v26, 0x200, v50
	v_cvt_pk_bf16_f32 v58, v20, v21
	v_cvt_pk_bf16_f32 v65, v6, v7
	s_nop 0
	s_nop 0
	v_ashrrev_i32_e32 v179, 4, v26
	v_pk_mul_f32 v[2:3], v[2:3], s[44:45] op_sel_hi:[1,0]
	v_cvt_pk_bf16_f32 v63, v4, v5
	s_nop 0
	s_nop 0
	s_nop 0
	v_add_u32_e32 v34, 0x300, v50
	s_nop 0
	s_nop 0
	s_nop 0
	v_ashrrev_i32_e32 v178, 4, v34
	s_nop 0
	s_nop 0
	v_add_u32_e32 v34, s37, v178
	v_cvt_pk_bf16_f32 v61, v2, v3
	s_nop 0
	s_nop 0
	s_nop 0
	s_nop 0
	s_nop 0
	v_mad_i64_i32 v[34:35], s[40:41], v34, s0, v[16:17]
	s_nop 0
	v_lshl_add_u64 v[34:35], v[34:35], 0, s[70:71]
	s_nop 0
	s_nop 0
	s_nop 0
	s_nop 0
	v_lshl_add_u64 v[34:35], v[34:35], 0, v[48:49]
	v_add_co_u32_e32 v40, vcc, s42, v34
	ds_bpermute_b32 v206, v28, v205
	ds_bpermute_b32 v208, v28, v207
	s_nop 0
	s_nop 0
	s_nop 0
	v_addc_co_u32_e32 v41, vcc, 0, v35, vcc
	v_and_b32_e32 v39, 0xffff0000, v10
	s_nop 0
	v_lshlrev_b32_e32 v38, 16, v10
	v_pk_mul_f32 v[44:45], v[38:39], s[44:45] op_sel_hi:[1,0]
	s_nop 0
	s_waitcnt vmcnt(7)
	v_mov_b32_e32 v0, v96
	v_mov_b32_e32 v1, v97
	v_mov_b32_e32 v2, v98
	v_mov_b32_e32 v3, v99
	s_waitcnt vmcnt(6)
	v_mov_b32_e32 v4, v100
	v_mov_b32_e32 v5, v101
	v_mov_b32_e32 v6, v102
	v_mov_b32_e32 v7, v103
	s_waitcnt vmcnt(5)
	v_mov_b32_e32 v18, v116
	v_mov_b32_e32 v19, v117
	v_mov_b32_e32 v20, v118
	v_mov_b32_e32 v21, v119
	s_waitcnt vmcnt(4)
	v_mov_b32_e32 v22, v120
	v_mov_b32_e32 v23, v121
	v_mov_b32_e32 v24, v122
	v_mov_b32_e32 v25, v123
	s_waitcnt vmcnt(3)
	v_mov_b32_e32 v26, v134
	v_mov_b32_e32 v27, v135
	v_mov_b32_e32 v28, v136
	v_mov_b32_e32 v29, v137
	s_waitcnt vmcnt(2)
	v_mov_b32_e32 v30, v138
	v_mov_b32_e32 v31, v139
	v_mov_b32_e32 v32, v140
	v_mov_b32_e32 v33, v141
	s_waitcnt vmcnt(1)
	v_mov_b32_e32 v34, v226
	v_mov_b32_e32 v35, v227
	v_mov_b32_e32 v36, v228
	v_mov_b32_e32 v37, v229
	s_waitcnt vmcnt(0)
	v_mov_b32_e32 v38, v230
	v_mov_b32_e32 v39, v231
	v_mov_b32_e32 v40, v232
	v_mov_b32_e32 v41, v233
	v_bfe_u32 v69, v9, 16, 1
	v_bfe_u32 v70, v8, 16, 1
	v_add3_u32 v70, v8, v70, s94
	v_add3_u32 v69, v9, v69, s94
	s_waitcnt vmcnt(8)
	v_and_b32_e32 v9, 0xffff0000, v12
	v_lshlrev_b32_e32 v8, 16, v12
	v_pk_mul_f32 v[8:9], v[8:9], s[44:45] op_sel_hi:[1,0]
	s_movk_i32 s37, 0x110
	v_bfe_u32 v75, v9, 16, 1
	v_bfe_u32 v76, v8, 16, 1
	v_add3_u32 v75, v9, v75, s94
	v_lshrrev_b32_e32 v9, 2, v50
	v_add3_u32 v76, v8, v76, s94
	v_bfe_u32 v8, v50, 2, 2
	v_and_b32_e32 v204, 12, v9
	v_or_b32_e32 v8, v204, v8
	v_mul_u32_u24_e32 v83, 0x120, v8
	v_lshlrev_b32_e32 v8, 4, v50
	v_mul_lo_u32 v209, v185, s37
	v_and_b32_e32 v210, 0xf0, v8
	v_add3_u32 v8, s17, v209, v210
	v_mul_lo_u32 v212, v180, s37
	v_mul_lo_u32 v213, v180, s39
	v_mul_lo_u32 v214, v179, s37
	v_mul_lo_u32 v215, v179, s39
	v_mul_lo_u32 v216, v178, s37
	v_mul_lo_u32 v217, v178, s39
	v_and_b32_e32 v47, 0xffff0000, v11
	v_lshlrev_b32_e32 v46, 16, v11
	v_pk_mul_f32 v[10:11], v[46:47], s[44:45] op_sel_hi:[1,0]
	v_lshlrev_b32_e32 v12, 16, v14
	v_cvt_pk_bf16_f32 v74, v10, v11
	v_and_b32_e32 v11, 0xffff0000, v13
	v_lshlrev_b32_e32 v10, 16, v13
	v_and_b32_e32 v13, 0xffff0000, v14
	v_bfe_u32 v67, v45, 16, 1
	v_pk_mul_f32 v[12:13], v[12:13], s[44:45] op_sel_hi:[1,0]
	v_bfe_u32 v68, v44, 16, 1
	v_add3_u32 v67, v45, v67, s94
	v_bfe_u32 v71, v43, 16, 1
	v_bfe_u32 v72, v42, 16, 1
	v_add3_u32 v68, v44, v68, s94
	v_add3_u32 v72, v42, v72, s94
	v_add3_u32 v71, v43, v71, s94
	v_and_b32_e32 v43, 0xffff0000, v15
	v_lshlrev_b32_e32 v42, 16, v15
	v_cvt_pk_bf16_f32 v80, v12, v13
	v_pk_mul_f32 v[10:11], v[10:11], s[44:45] op_sel_hi:[1,0]
	s_waitcnt vmcnt(7)
	ds_write_b128 v8, v[0:3]
	v_add3_u32 v0, s17, v211, v210
	s_waitcnt vmcnt(6)
	ds_write_b128 v0, v[4:7] offset:17408
	v_add3_u32 v0, s17, v212, v210
	v_add_u32_e32 v8, s38, v180
	v_mad_i64_i32 v[8:9], s[40:41], v8, s0, v[16:17]
	v_lshl_add_u64 v[8:9], v[8:9], 0, s[70:71]
	v_lshl_add_u64 v[8:9], v[8:9], 0, v[48:49]
	s_waitcnt vmcnt(5)
	ds_write_b128 v0, v[18:21]
	v_add3_u32 v0, s17, v213, v210
	s_waitcnt vmcnt(4)
	ds_write_b128 v0, v[22:25] offset:17408
	v_add3_u32 v0, s17, v214, v210
	v_add_u32_e32 v18, s38, v179
	v_mad_i64_i32 v[18:19], s[40:41], v18, s0, v[16:17]
	v_lshl_add_u64 v[18:19], v[18:19], 0, s[70:71]
	s_waitcnt vmcnt(3)
	ds_write_b128 v0, v[26:29]
	v_add3_u32 v0, s17, v215, v210
	s_waitcnt vmcnt(2)
	ds_write_b128 v0, v[30:33] offset:17408
	v_add3_u32 v0, s17, v216, v210
	v_lshl_add_u64 v[18:19], v[18:19], 0, v[48:49]
	s_waitcnt vmcnt(1)
	ds_write_b128 v0, v[34:37]
	v_add3_u32 v0, s17, v217, v210
	v_pk_mul_f32 v[14:15], v[42:43], s[44:45] op_sel_hi:[1,0]
	s_waitcnt vmcnt(0)
	ds_write_b128 v0, v[38:41] offset:17408
	v_add_u32_e32 v0, s38, v185
	v_mad_i64_i32 v[0:1], s[40:41], v0, s0, v[16:17]
	v_lshl_add_u64 v[0:1], v[0:1], 0, s[70:71]
	v_lshl_add_u64 v[0:1], v[0:1], 0, v[48:49]
	v_add_co_u32_e32 v4, vcc, s42, v0
	s_nop 0
	s_nop 0
	v_addc_co_u32_e32 v5, vcc, 0, v1, vcc
	v_add_co_u32_e32 v12, vcc, s42, v8
	s_nop 0
	s_nop 0
	v_addc_co_u32_e32 v13, vcc, 0, v9, vcc
	v_add_co_u32_e32 v18, vcc, s42, v18
	s_nop 1
	v_addc_co_u32_e32 v19, vcc, 0, v19, vcc
	v_cvt_pk_bf16_f32 v78, v10, v11
	v_cvt_pk_bf16_f32 v82, v14, v15
	global_load_dwordx4 v[0:3], v[4:5], off offset:2048
	s_nop 0
	global_load_dwordx4 v[4:7], v[4:5], off offset:3072
	s_nop 0
	global_load_dwordx4 v[8:11], v[12:13], off offset:2048
	s_nop 0
	global_load_dwordx4 v[12:15], v[12:13], off offset:3072
	s_nop 0
	global_load_dwordx4 v[20:23], v[18:19], off offset:2048
	global_load_dwordx4 v[28:31], v[18:19], off offset:3072
	v_add_u32_e32 v18, s38, v178
	v_mad_i64_i32 v[16:17], s[38:39], v18, s0, v[16:17]
	v_lshl_add_u64 v[16:17], v[16:17], 0, s[70:71]
	v_lshl_add_u64 v[16:17], v[16:17], 0, v[48:49]
	v_add_co_u32_e32 v16, vcc, s42, v16
	v_mul_u32_u24_e32 v49, 0x110, v183
	s_nop 0
	v_addc_co_u32_e32 v17, vcc, 0, v17, vcc
	global_load_dwordx4 v[40:43], v[16:17], off offset:2048
	global_load_dwordx4 v[44:47], v[16:17], off offset:3072
	v_add3_u32 v219, s17, v160, v49
	v_add_u32_e32 v49, s23, v178
	v_add_u32_e32 v49, 0xffffc080, v49
	v_mov_b32_e32 v16, v51
	v_mad_i64_i32 v[50:51], s[38:39], v49, s0, 0
	s_and_b32 s38, s36, 0x300
	v_add_u32_e32 v49, s23, v179
	v_readlane_b32 s37, v251, 56
	v_or3_b32 v50, v50, s38, v48
	v_add_u32_e32 v49, 0xffffc080, v49
	v_add3_u32 v218, v84, s37, v83
	v_lshl_add_u64 v[134:135], s[30:31], 0, v[50:51]
	v_mad_i64_i32 v[50:51], s[36:37], v49, s0, 0
	v_add_u32_e32 v49, s23, v180
	v_or3_b32 v50, v50, s38, v48
	v_add_u32_e32 v49, 0xffffc080, v49
	v_lshl_add_u64 v[136:137], s[30:31], 0, v[50:51]
	v_mad_i64_i32 v[50:51], s[36:37], v49, s0, 0
	v_add_u32_e32 v49, s23, v185
	v_or3_b32 v50, v50, s38, v48
	v_add_u32_e32 v49, 0xffffc080, v49
	v_lshl_add_u64 v[138:139], s[30:31], 0, v[50:51]
	v_mad_i64_i32 v[50:51], s[36:37], v49, s0, 0
	v_or3_b32 v50, v50, s38, v48
	v_mov_b32_e32 v48, 0
	v_mov_b32_e32 v19, v58
	v_perm_b32 v18, v56, v55, s95
	v_perm_b32 v17, v54, v53, s95
	v_mov_b32_e32 v27, v65
	v_mov_b32_e32 v26, v63
	v_mov_b32_e32 v25, v61
	v_mov_b32_e32 v24, v60
	v_mov_b32_e32 v35, v74
	v_perm_b32 v34, v67, v68, s95
	v_perm_b32 v33, v69, v70, s95
	v_perm_b32 v32, v71, v72, s95
	v_mov_b32_e32 v39, v82
	v_mov_b32_e32 v38, v80
	v_mov_b32_e32 v37, v78
	v_perm_b32 v36, v75, v76, s95
	v_lshl_add_u64 v[140:141], s[30:31], 0, v[50:51]
	s_mov_b64 s[36:37], 0
	v_mov_b32_e32 v49, v48
	v_mov_b32_e32 v50, v48
	v_mov_b32_e32 v51, v48
	v_mov_b32_e32 v52, v48
	v_mov_b32_e32 v53, v48
	v_mov_b32_e32 v54, v48
	v_mov_b32_e32 v55, v48
	v_mov_b32_e32 v68, v48
	v_mov_b32_e32 v69, v48
	v_mov_b32_e32 v70, v48
	v_mov_b32_e32 v71, v48
	v_mov_b32_e32 v76, v48
	v_mov_b32_e32 v77, v48
	v_mov_b32_e32 v78, v48
	v_mov_b32_e32 v79, v48
	v_mov_b32_e32 v80, v48
	v_mov_b32_e32 v81, v48
	v_mov_b32_e32 v82, v48
	v_mov_b32_e32 v83, v48
	v_mov_b32_e32 v84, v48
	v_mov_b32_e32 v85, v48
	v_mov_b32_e32 v86, v48
	v_mov_b32_e32 v87, v48
	v_mov_b32_e32 v88, v48
	v_mov_b32_e32 v89, v48
	v_mov_b32_e32 v90, v48
	v_mov_b32_e32 v91, v48
	v_mov_b32_e32 v96, v48
	v_mov_b32_e32 v97, v48
	v_mov_b32_e32 v98, v48
	v_mov_b32_e32 v99, v48
	v_mov_b32_e32 v92, v48
	v_mov_b32_e32 v93, v48
	v_mov_b32_e32 v94, v48
	v_mov_b32_e32 v95, v48
	v_mov_b32_e32 v100, v48
	v_mov_b32_e32 v101, v48
	v_mov_b32_e32 v102, v48
	v_mov_b32_e32 v103, v48
	v_mov_b32_e32 v104, v48
	v_mov_b32_e32 v105, v48
	v_mov_b32_e32 v106, v48
	v_mov_b32_e32 v107, v48
	v_mov_b32_e32 v108, v48
	v_mov_b32_e32 v109, v48
	v_mov_b32_e32 v110, v48
	v_mov_b32_e32 v111, v48
	v_mov_b32_e32 v72, v48
	v_mov_b32_e32 v73, v48
	v_mov_b32_e32 v74, v48
	v_mov_b32_e32 v75, v48
	v_mov_b32_e32 v64, v48
	v_mov_b32_e32 v65, v48
	v_mov_b32_e32 v66, v48
	v_mov_b32_e32 v67, v48
	v_mov_b32_e32 v60, v48
	v_mov_b32_e32 v61, v48
	v_mov_b32_e32 v62, v48
	v_mov_b32_e32 v63, v48
	v_mov_b32_e32 v56, v48
	v_mov_b32_e32 v57, v48
	v_mov_b32_e32 v58, v48
	v_mov_b32_e32 v59, v48
	v_mov_b32_e32 v132, v48
	v_mov_b32_e32 v133, v48
	s_waitcnt lgkmcnt(0)
	s_barrier
	s_branch .LBB0_699

.LBB0_751:
	s_andn2_b64 vcc, exec, s[36:37]
	s_cbranch_vccnz .LBB0_774
	v_mov_b32_e32 v56, v189
	v_readlane_b32 s36, v251, 47
	v_and_b32_e32 v0, 63, v56
	v_lshlrev_b32_e32 v0, 2, v0
	v_readlane_b32 s37, v251, 48
	s_nop 4
	global_load_dword v16, v0, s[36:37]
	global_load_dword v17, v0, s[36:37] offset:256
	global_load_dword v18, v0, s[36:37] offset:512
	global_load_dword v19, v0, s[36:37] offset:768
	s_add_i32 s20, s19, 0xffffff00
	s_lshr_b32 s38, s20, 6
	s_lshl_b32 s20, s19, 6
	s_lshl_b32 s23, s38, 10
	s_and_b32 s20, s20, 0x3c0
	s_or_b32 s20, s23, s20
	v_ashrrev_i32_e32 v0, 2, v56
	s_addk_i32 s20, 0x1000
	v_and_b32_e32 v206, -16, v0
	v_and_b32_e32 v204, 15, v56
	v_add_u32_e32 v0, s20, v206
	s_lshl_b32 s21, s19, 3
	v_or_b32_e32 v2, v0, v204
	v_mov_b64_e32 v[0:1], s[6:7]
	s_and_b32 s21, s21, 0x180
	v_mad_i64_i32 v[0:1], s[36:37], v2, s0, v[0:1]
	s_lshl_b32 s36, s21, 1
	s_mov_b32 s37, s71
	v_lshl_add_u64 v[0:1], v[0:1], 0, s[36:37]
	v_and_b32_e32 v160, 48, v56
	v_lshl_add_u64 v[4:5], v[0:1], 0, v[160:161]
	s_movk_i32 s22, 0x1000
	v_add_co_u32_e32 v0, vcc, s22, v4
	v_mbcnt_hi_u32_b32 v151, -1, v194
	s_nop 0
	v_addc_co_u32_e32 v1, vcc, 0, v5, vcc
	global_load_dwordx4 v[0:3], v[0:1], off offset:1024
	v_and_b32_e32 v8, 64, v151
	s_mov_b64 s[36:37], 0x1400
	v_xor_b32_e32 v9, 32, v151
	v_add_u32_e32 v208, 64, v8
	v_lshl_add_u64 v[12:13], v[4:5], 0, s[36:37]
	v_xor_b32_e32 v10, 16, v151
	v_cmp_lt_i32_e32 vcc, v9, v208
	global_load_dwordx4 v[4:7], v[12:13], off offset:64
	v_xor_b32_e32 v11, 8, v151
	v_cndmask_b32_e32 v8, v151, v9, vcc
	v_cmp_lt_i32_e32 vcc, v10, v208
	v_lshlrev_b32_e32 v141, 2, v8
	v_xor_b32_e32 v14, 4, v151
	v_cndmask_b32_e32 v9, v151, v10, vcc
	v_cmp_lt_i32_e32 vcc, v11, v208
	v_lshlrev_b32_e32 v205, 2, v9
	s_mov_b32 s40, 0x3e000000
	v_cndmask_b32_e32 v10, v151, v11, vcc
	v_lshlrev_b32_e32 v22, 2, v10
	global_load_dwordx4 v[8:11], v[12:13], off offset:128
	v_cmp_lt_i32_e32 vcc, v14, v208
	v_xor_b32_e32 v15, 2, v151
	s_lshl_b32 s36, s38, 19
	v_cndmask_b32_e32 v14, v151, v14, vcc
	v_lshlrev_b32_e32 v25, 2, v14
	v_cmp_lt_i32_e32 vcc, v15, v208
	v_readlane_b32 s37, v251, 42
	v_ashrrev_i32_e32 v138, 4, v56
	v_cndmask_b32_e32 v15, v151, v15, vcc
	v_lshlrev_b32_e32 v26, 2, v15
	global_load_dwordx4 v[12:15], v[12:13], off offset:192
	s_or_b32 s36, s36, s37
	v_ashrrev_i32_e32 v139, 31, v138
	s_or_b32 s70, s36, s21
	v_lshlrev_b64 v[42:43], 9, v[138:139]
	v_lshlrev_b32_e32 v140, 3, v204
	v_readlane_b32 s36, v252, 55
	v_readlane_b32 s38, v252, 57
	v_readlane_b32 s37, v252, 56
	v_readlane_b32 s39, v252, 58
	v_or_b32_e32 v44, s70, v140
	v_mov_b32_e32 v45, v161
	s_barrier
	v_lshlrev_b32_e32 v207, 3, v56
	s_mov_b32 s22, 0
	v_mov_b32_e32 v154, 0xf149f2ca
	s_waitcnt vmcnt(8)
	v_lshl_add_u64 v[84:85], v[42:43], 0, s[70:71]
	v_or_b32_e32 v84, v84, v140
	v_lshlrev_b64 v[86:87], 1, v[84:85]
	v_lshl_add_u64 v[88:89], s[36:37], 0, v[86:87]
	global_load_dwordx4 v[90:93], v[88:89], off
	v_lshl_add_u64 v[94:95], s[38:39], 0, v[86:87]
	global_load_dwordx4 v[96:99], v[94:95], off
	v_add_u32_e32 v102, 0x100, v56
	v_ashrrev_i32_e32 v100, 4, v102
	v_ashrrev_i32_e32 v101, 31, v100
	v_lshlrev_b64 v[104:105], 9, v[100:101]
	v_lshl_add_u64 v[106:107], v[104:105], 0, v[44:45]
	v_lshlrev_b64 v[46:47], 1, v[106:107]
	v_lshl_add_u64 v[108:109], s[36:37], 0, v[46:47]
	global_load_dwordx4 v[114:117], v[108:109], off
	v_lshl_add_u64 v[110:111], s[38:39], 0, v[46:47]
	global_load_dwordx4 v[118:121], v[110:111], off
	v_add_u32_e32 v103, 0x200, v56
	v_ashrrev_i32_e32 v122, 4, v103
	v_ashrrev_i32_e32 v123, 31, v122
	v_lshlrev_b64 v[124:125], 9, v[122:123]
	v_lshl_add_u64 v[126:127], v[124:125], 0, v[44:45]
	v_lshlrev_b64 v[48:49], 1, v[126:127]
	v_lshl_add_u64 v[128:129], s[36:37], 0, v[48:49]
	global_load_dwordx4 v[216:219], v[128:129], off
	v_lshl_add_u64 v[130:131], s[38:39], 0, v[48:49]
	global_load_dwordx4 v[220:223], v[130:131], off
	v_add_u32_e32 v226, 0x300, v56
	v_ashrrev_i32_e32 v224, 4, v226
	v_ashrrev_i32_e32 v225, 31, v224
	v_lshlrev_b64 v[228:229], 9, v[224:225]
	v_lshl_add_u64 v[230:231], v[228:229], 0, v[44:45]
	v_lshlrev_b64 v[50:51], 1, v[230:231]
	v_lshl_add_u64 v[232:233], s[36:37], 0, v[50:51]
	global_load_dwordx4 v[234:237], v[232:233], off
	v_lshl_add_u64 v[238:239], s[38:39], 0, v[50:51]
	global_load_dwordx4 v[240:243], v[238:239], off
	s_waitcnt vmcnt(14)
	v_mul_f32_e32 v20, v16, v17
	ds_bpermute_b32 v23, v141, v20
	s_waitcnt vmcnt(12)
	v_mul_f32_e32 v21, v18, v19
	ds_bpermute_b32 v24, v141, v21
	v_mov_b32_e32 v112, 0xf149f2ca
	s_mov_b64 s[42:43], 0x1800
	s_waitcnt lgkmcnt(1)
	v_fmac_f32_e32 v23, v16, v17
	ds_bpermute_b32 v27, v205, v23
	s_waitcnt lgkmcnt(1)
	v_fmac_f32_e32 v24, v18, v19
	ds_bpermute_b32 v28, v205, v24
	s_mov_b64 s[44:45], 0x1c00
	s_mov_b64 s[46:47], 0xf7c0000
	s_waitcnt lgkmcnt(1)
	v_add_f32_e32 v23, v23, v27
	ds_bpermute_b32 v27, v22, v23
	s_waitcnt lgkmcnt(1)
	v_add_f32_e32 v24, v24, v28
	ds_bpermute_b32 v22, v22, v24
	s_mov_b64 s[48:49], 0xfbc0000
	s_waitcnt lgkmcnt(0)
	v_add_f32_e32 v22, v24, v22
	ds_bpermute_b32 v24, v25, v22
	s_waitcnt lgkmcnt(0)
	v_add_f32_e32 v212, v22, v24
	ds_bpermute_b32 v213, v26, v212
	s_waitcnt vmcnt(11)
	v_and_b32_e32 v17, 0xffff0000, v0
	v_lshlrev_b32_e32 v16, 16, v0
	v_and_b32_e32 v19, 0xffff0000, v1
	v_lshlrev_b32_e32 v18, 16, v1
	v_and_b32_e32 v1, 0xffff0000, v2
	v_lshlrev_b32_e32 v0, 16, v2
	v_and_b32_e32 v21, 0xffff0000, v3
	v_lshlrev_b32_e32 v20, 16, v3
	v_pk_mul_f32 v[2:3], v[16:17], s[40:41] op_sel_hi:[1,0]
	v_pk_mul_f32 v[0:1], v[0:1], s[40:41] op_sel_hi:[1,0]
	v_bfe_u32 v33, v2, 16, 1
	v_add3_u32 v57, v2, v33, s94
	v_add_f32_e32 v2, v23, v27
	ds_bpermute_b32 v23, v25, v2
	v_cvt_pk_bf16_f32 v62, v0, v1
	s_waitcnt vmcnt(10)
	v_and_b32_e32 v1, 0xffff0000, v4
	v_lshlrev_b32_e32 v0, 16, v4
	v_pk_mul_f32 v[0:1], v[0:1], s[40:41] op_sel_hi:[1,0]
	v_pk_mul_f32 v[16:17], v[18:19], s[40:41] op_sel_hi:[1,0]
	s_waitcnt lgkmcnt(0)
	v_add_f32_e32 v210, v2, v23
	v_cvt_pk_bf16_f32 v74, v0, v1
	s_waitcnt vmcnt(9)
	v_and_b32_e32 v1, 0xffff0000, v8
	v_lshlrev_b32_e32 v0, 16, v8
	v_bfe_u32 v28, v3, 16, 1
	v_cvt_pk_bf16_f32 v60, v16, v17
	v_and_b32_e32 v17, 0xffff0000, v7
	v_lshlrev_b32_e32 v16, 16, v7
	v_pk_mul_f32 v[40:41], v[0:1], s[40:41] op_sel_hi:[1,0]
	v_and_b32_e32 v1, 0xffff0000, v9
	v_lshlrev_b32_e32 v0, 16, v9
	v_and_b32_e32 v37, 0xffff0000, v10
	v_lshlrev_b32_e32 v36, 16, v10
	v_add_u32_e32 v10, 0x100, v56
	v_pk_mul_f32 v[18:19], v[20:21], s[40:41] op_sel_hi:[1,0]
	v_add3_u32 v58, v3, v28, s94
	v_and_b32_e32 v3, 0xffff0000, v5
	v_lshlrev_b32_e32 v2, 16, v5
	v_and_b32_e32 v5, 0xffff0000, v6
	v_lshlrev_b32_e32 v4, 16, v6
	v_pk_mul_f32 v[6:7], v[16:17], s[40:41] op_sel_hi:[1,0]
	v_pk_mul_f32 v[8:9], v[0:1], s[40:41] op_sel_hi:[1,0]
	v_lshl_add_u64 v[0:1], v[42:43], 0, s[70:71]
	v_ashrrev_i32_e32 v136, 4, v10
	v_pk_mul_f32 v[2:3], v[2:3], s[40:41] op_sel_hi:[1,0]
	v_pk_mul_f32 v[4:5], v[4:5], s[40:41] op_sel_hi:[1,0]
	v_or_b32_e32 v0, v0, v140
	v_ashrrev_i32_e32 v137, 31, v136
	v_add_u32_e32 v10, 0x200, v56
	v_cvt_pk_bf16_f32 v72, v18, v19
	v_cvt_pk_bf16_f32 v80, v6, v7
	v_lshlrev_b64 v[0:1], 1, v[0:1]
	v_lshlrev_b64 v[16:17], 9, v[136:137]
	v_ashrrev_i32_e32 v134, 4, v10
	v_add_u32_e32 v10, 0x300, v56
	v_cvt_pk_bf16_f32 v76, v2, v3
	v_cvt_pk_bf16_f32 v78, v4, v5
	s_nop 0
	s_nop 0
	v_lshl_add_u64 v[16:17], v[16:17], 0, v[44:45]
	v_ashrrev_i32_e32 v135, 31, v134
	v_ashrrev_i32_e32 v132, 4, v10
	s_nop 0
	s_nop 0
	s_nop 0
	v_lshlrev_b64 v[46:47], 1, v[16:17]
	v_lshlrev_b64 v[24:25], 9, v[134:135]
	v_ashrrev_i32_e32 v133, 31, v132
	s_nop 0
	s_nop 0
	v_lshl_add_u64 v[24:25], v[24:25], 0, v[44:45]
	v_lshlrev_b64 v[32:33], 9, v[132:133]
	s_nop 0
	s_nop 0
	s_nop 0
	v_lshlrev_b64 v[48:49], 1, v[24:25]
	v_lshl_add_u64 v[32:33], v[32:33], 0, v[44:45]
	s_nop 0
	s_nop 0
	v_lshlrev_b64 v[50:51], 1, v[32:33]
	ds_bpermute_b32 v211, v26, v210
	s_nop 0
	s_nop 0
	s_nop 0
	s_nop 0
	s_nop 0
	v_pk_mul_f32 v[52:53], v[36:37], s[40:41] op_sel_hi:[1,0]
	s_nop 0
	s_nop 0
	s_waitcnt vmcnt(7)
	v_mov_b32_e32 v0, v90
	v_mov_b32_e32 v1, v91
	v_mov_b32_e32 v2, v92
	v_mov_b32_e32 v3, v93
	s_waitcnt vmcnt(6)
	v_mov_b32_e32 v4, v96
	v_mov_b32_e32 v5, v97
	v_mov_b32_e32 v6, v98
	v_mov_b32_e32 v7, v99
	s_waitcnt vmcnt(5)
	v_mov_b32_e32 v16, v114
	v_mov_b32_e32 v17, v115
	v_mov_b32_e32 v18, v116
	v_mov_b32_e32 v19, v117
	s_waitcnt vmcnt(4)
	v_mov_b32_e32 v20, v118
	v_mov_b32_e32 v21, v119
	v_mov_b32_e32 v22, v120
	v_mov_b32_e32 v23, v121
	s_waitcnt vmcnt(3)
	v_mov_b32_e32 v24, v216
	v_mov_b32_e32 v25, v217
	v_mov_b32_e32 v26, v218
	v_mov_b32_e32 v27, v219
	s_waitcnt vmcnt(2)
	v_mov_b32_e32 v28, v220
	v_mov_b32_e32 v29, v221
	v_mov_b32_e32 v30, v222
	v_mov_b32_e32 v31, v223
	s_waitcnt vmcnt(1)
	v_mov_b32_e32 v32, v234
	v_mov_b32_e32 v33, v235
	v_mov_b32_e32 v34, v236
	v_mov_b32_e32 v35, v237
	s_waitcnt vmcnt(0)
	v_mov_b32_e32 v36, v240
	v_mov_b32_e32 v37, v241
	v_mov_b32_e32 v38, v242
	v_mov_b32_e32 v39, v243
	v_and_b32_e32 v55, 0xffff0000, v11
	v_lshlrev_b32_e32 v54, 16, v11
	v_pk_mul_f32 v[10:11], v[54:55], s[40:41] op_sel_hi:[1,0]
	v_bfe_u32 v54, v11, 16, 1
	v_bfe_u32 v55, v10, 16, 1
	v_add3_u32 v55, v10, v55, s94
	v_add3_u32 v54, v11, v54, s94
	s_waitcnt vmcnt(8)
	v_and_b32_e32 v11, 0xffff0000, v13
	v_lshlrev_b32_e32 v10, 16, v13
	v_pk_mul_f32 v[10:11], v[10:11], s[40:41] op_sel_hi:[1,0]
	v_cvt_pk_bf16_f32 v82, v40, v41
	v_cvt_pk_bf16_f32 v84, v8, v9
	v_and_b32_e32 v9, 0xffff0000, v12
	v_lshlrev_b32_e32 v8, 16, v12
	v_and_b32_e32 v13, 0xffff0000, v14
	v_lshlrev_b32_e32 v12, 16, v14
	v_and_b32_e32 v41, 0xffff0000, v15
	v_lshlrev_b32_e32 v40, 16, v15
	v_bfe_u32 v67, v10, 16, 1
	v_pk_mul_f32 v[8:9], v[8:9], s[40:41] op_sel_hi:[1,0]
	v_pk_mul_f32 v[12:13], v[12:13], s[40:41] op_sel_hi:[1,0]
	v_pk_mul_f32 v[14:15], v[40:41], s[40:41] op_sel_hi:[1,0]
	v_add3_u32 v87, v10, v67, s94
	s_movk_i32 s40, 0x110
	v_lshlrev_b32_e32 v10, 4, v56
	v_mul_lo_u32 v214, v138, s40
	v_and_b32_e32 v215, 0xf0, v10
	s_movk_i32 s41, 0x120
	v_add3_u32 v10, s17, v214, v215
	v_mul_lo_u32 v216, v138, s41
	v_mul_lo_u32 v217, v136, s40
	v_mul_lo_u32 v218, v136, s41
	v_mul_lo_u32 v219, v134, s40
	v_mul_lo_u32 v220, v134, s41
	v_mul_lo_u32 v221, v132, s40
	v_mul_lo_u32 v222, v132, s41
	s_mov_b64 s[40:41], 0x10000
	v_cvt_pk_bf16_f32 v14, v14, v15
	v_cvt_pk_bf16_f32 v52, v52, v53
	v_bfe_u32 v66, v11, 16, 1
	v_cvt_pk_bf16_f32 v86, v8, v9
	s_waitcnt vmcnt(7)
	ds_write_b128 v10, v[0:3]
	v_add3_u32 v0, s17, v216, v215
	s_waitcnt vmcnt(6)
	ds_write_b128 v0, v[4:7] offset:17408
	v_add3_u32 v0, s17, v217, v215
	v_add3_u32 v88, v11, v66, s94
	v_cvt_pk_bf16_f32 v12, v12, v13
	v_lshrrev_b32_e32 v9, 2, v56
	s_waitcnt vmcnt(5)
	ds_write_b128 v0, v[16:19]
	v_add3_u32 v0, s17, v218, v215
	s_waitcnt vmcnt(4)
	ds_write_b128 v0, v[20:23] offset:17408
	v_add3_u32 v0, s17, v219, v215
	v_bfe_u32 v8, v56, 2, 2
	v_and_b32_e32 v209, 12, v9
	v_or_b32_e32 v8, v209, v8
	s_waitcnt vmcnt(3)
	ds_write_b128 v0, v[24:27]
	v_add3_u32 v0, s17, v220, v215
	s_waitcnt vmcnt(2)
	ds_write_b128 v0, v[28:31] offset:17408
	v_add3_u32 v0, s17, v221, v215
	s_waitcnt vmcnt(1)
	ds_write_b128 v0, v[32:35]
	v_add3_u32 v0, s17, v222, v215
	s_waitcnt vmcnt(0)
	ds_write_b128 v0, v[36:39] offset:17408
	v_lshl_add_u64 v[0:1], v[42:43], 0, v[44:45]
	v_lshl_add_u64 v[0:1], v[0:1], 1, v[166:167]
	v_lshl_add_u64 v[2:3], s[36:37], 0, v[0:1]
	v_lshl_add_u64 v[0:1], s[38:39], 0, v[0:1]
	global_load_dwordx4 v[16:19], v[2:3], off
	global_load_dwordx4 v[20:23], v[0:1], off
	v_lshl_add_u64 v[0:1], v[46:47], 0, s[40:41]
	v_lshl_add_u64 v[2:3], s[36:37], 0, v[0:1]
	v_lshl_add_u64 v[0:1], s[38:39], 0, v[0:1]
	global_load_dwordx4 v[24:27], v[2:3], off
	global_load_dwordx4 v[28:31], v[0:1], off
	v_lshl_add_u64 v[0:1], v[48:49], 0, s[40:41]
	v_lshl_add_u64 v[2:3], s[36:37], 0, v[0:1]
	v_lshl_add_u64 v[0:1], s[38:39], 0, v[0:1]
	global_load_dwordx4 v[36:39], v[2:3], off
	global_load_dwordx4 v[40:43], v[0:1], off
	v_lshl_add_u64 v[0:1], v[50:51], 0, s[40:41]
	v_lshl_add_u64 v[2:3], s[36:37], 0, v[0:1]
	v_lshl_add_u64 v[0:1], s[38:39], 0, v[0:1]
	global_load_dwordx4 v[64:67], v[2:3], off
	global_load_dwordx4 v[68:71], v[0:1], off
	v_mul_u32_u24_e32 v32, 0x110, v204
	v_add3_u32 v224, s17, v160, v32
	v_lshlrev_b64 v[32:33], 10, v[132:133]
	v_lshlrev_b32_e32 v160, 1, v44
	v_lshl_add_u64 v[32:33], v[32:33], 0, v[160:161]
	v_lshl_add_u64 v[144:145], s[30:31], 0, v[32:33]
	v_add_u32_e32 v32, s23, v132
	v_add_u32_e32 v133, 0xe80, v32
	v_lshlrev_b64 v[32:33], 10, v[134:135]
	v_lshl_add_u64 v[32:33], v[32:33], 0, v[160:161]
	v_lshl_add_u64 v[146:147], s[30:31], 0, v[32:33]
	v_add_u32_e32 v32, s23, v134
	v_add_u32_e32 v135, 0xe80, v32
	v_lshlrev_b64 v[32:33], 10, v[136:137]
	v_lshl_add_u64 v[32:33], v[32:33], 0, v[160:161]
	v_lshl_add_u64 v[148:149], s[30:31], 0, v[32:33]
	v_add_u32_e32 v32, s23, v136
	v_add_u32_e32 v137, 0xe80, v32
	v_lshlrev_b64 v[32:33], 10, v[138:139]
	v_lshl_add_u64 v[32:33], v[32:33], 0, v[160:161]
	v_lshl_add_u64 v[152:153], s[30:31], 0, v[32:33]
	v_add_u32_e32 v32, s23, v138
	v_mul_u32_u24_e32 v8, 0x120, v8
	v_and_b32_e32 v9, 24, v207
	v_readlane_b32 s36, v251, 56
	v_add_u32_e32 v139, 0xe80, v32
	v_mov_b32_e32 v32, 0
	v_add3_u32 v223, v9, s36, v8
	v_mov_b32_e32 v3, v72
	v_mov_b32_e32 v2, v62
	v_mov_b32_e32 v1, v60
	v_perm_b32 v0, v58, v57, s95
	v_mov_b32_e32 v7, v80
	v_mov_b32_e32 v6, v78
	v_mov_b32_e32 v5, v76
	v_mov_b32_e32 v4, v74
	v_perm_b32 v11, v54, v55, s95
	v_mov_b32_e32 v10, v52
	v_mov_b32_e32 v9, v84
	v_mov_b32_e32 v8, v82
	v_mov_b32_e32 v15, v14
	v_mov_b32_e32 v14, v12
	v_perm_b32 v13, v88, v87, s95
	v_mov_b32_e32 v12, v86
	s_mov_b64 s[38:39], 0
	v_mov_b32_e32 v33, v32
	v_mov_b32_e32 v34, v32
	v_mov_b32_e32 v35, v32
	v_mov_b32_e32 v44, v32
	v_mov_b32_e32 v45, v32
	v_mov_b32_e32 v46, v32
	v_mov_b32_e32 v47, v32
	v_mov_b32_e32 v60, v32
	v_mov_b32_e32 v61, v32
	v_mov_b32_e32 v62, v32
	v_mov_b32_e32 v63, v32
	v_mov_b32_e32 v76, v32
	v_mov_b32_e32 v77, v32
	v_mov_b32_e32 v78, v32
	v_mov_b32_e32 v79, v32
	v_mov_b32_e32 v80, v32
	v_mov_b32_e32 v81, v32
	v_mov_b32_e32 v82, v32
	v_mov_b32_e32 v83, v32
	v_mov_b32_e32 v84, v32
	v_mov_b32_e32 v85, v32
	v_mov_b32_e32 v86, v32
	v_mov_b32_e32 v87, v32
	v_mov_b32_e32 v88, v32
	v_mov_b32_e32 v89, v32
	v_mov_b32_e32 v90, v32
	v_mov_b32_e32 v91, v32
	v_mov_b32_e32 v96, v32
	v_mov_b32_e32 v97, v32
	v_mov_b32_e32 v98, v32
	v_mov_b32_e32 v99, v32
	v_mov_b32_e32 v92, v32
	v_mov_b32_e32 v93, v32
	v_mov_b32_e32 v94, v32
	v_mov_b32_e32 v95, v32
	v_mov_b32_e32 v100, v32
	v_mov_b32_e32 v101, v32
	v_mov_b32_e32 v102, v32
	v_mov_b32_e32 v103, v32
	v_mov_b32_e32 v104, v32
	v_mov_b32_e32 v105, v32
	v_mov_b32_e32 v106, v32
	v_mov_b32_e32 v107, v32
	v_mov_b32_e32 v108, v32
	v_mov_b32_e32 v109, v32
	v_mov_b32_e32 v110, v32
	v_mov_b32_e32 v111, v32
	v_mov_b32_e32 v72, v32
	v_mov_b32_e32 v73, v32
	v_mov_b32_e32 v74, v32
	v_mov_b32_e32 v75, v32
	v_mov_b32_e32 v56, v32
	v_mov_b32_e32 v57, v32
	v_mov_b32_e32 v58, v32
	v_mov_b32_e32 v59, v32
	v_mov_b32_e32 v52, v32
	v_mov_b32_e32 v53, v32
	v_mov_b32_e32 v54, v32
	v_mov_b32_e32 v55, v32
	v_mov_b32_e32 v48, v32
	v_mov_b32_e32 v49, v32
	v_mov_b32_e32 v50, v32
	v_mov_b32_e32 v51, v32
	v_mov_b32_e32 v142, v32
	v_mov_b32_e32 v143, v32
	s_waitcnt lgkmcnt(0)
	s_barrier
	s_branch .LBB0_755
